# out-projection epilogue pass 1: residual loads 12 deep in flight with the non-temporal hint (on top of the nt x loads in the row pass)
# speedup vs baseline: 1.0059x; 1.0059x over previous
; __device__ __forceinline__ unsigned cvt_pk_bf16(float lo, float hi) { unsigned r; asm volatile("v_cvt_pk_bf16_f32 %0, %1, %2" : "=v"(r) : "v"(lo), "v"(hi)); return r; }
;     __device__ __forceinline__ void fused(f32x4 (&acc)[2][2][4][2], const Unit& u, int wr, int wc, int fr, int fq, LAS unsigned char* lds, int wid, int lane) const {
;         const int row0 = u.pm * BM + wr * 64 + fr, col0 = u.pn * BM + wc * 32 + 4 * fq, b = u.pm >> 3;
;         const float* modb = mod + (size_t)b * NMOD + col0;
;         { f32x4 gv[2][2];
; #pragma unroll
;           for (int bj = 0; bj < 2; ++bj)
; #pragma unroll
;             for (int n = 0; n < 2; ++n) gv[bj][n] = *(const f32x4*)(modb + gate_off + bj * HALF + n * 16);
; #pragma unroll
;           for (int ai = 0; ai < 2; ++ai)
; #pragma unroll
;             for (int m = 0; m < 4; ++m) { const size_t off = (size_t)(row0 + ai * HALF + m * 16) * DM + col0;
; #pragma unroll
;                 for (int bj = 0; bj < 2; ++bj)
; #pragma unroll
;                     for (int n = 0; n < 2; ++n) { const f32x4 xv = *(const f32x4*)(base + off + bj * HALF + n * 16); const f32x4 o = xv + gv[bj][n] * acc[ai][bj][m][n];
;                         u32x2 w; w.x = cvt_pk_bf16(o[0], o[1]); w.y = cvt_pk_bf16(o[2], o[3]); *(u32x2*)(x1b + off + bj * HALF + n * 16) = w; acc[ai][bj][m][n] = o; }
;                 asm volatile("" ::: "memory"); } }
.LBB0_582:
	s_add_u32 s0, s34, 0xd200000
	s_addc_u32 s1, s35, 0
	s_lshl_b32 s11, s7, 5
	s_lshl_b32 s12, s8, 8
	s_or_b32 s11, s12, s11
	s_lshl_b32 s10, s6, 8
	v_and_or_b32 v144, v140, 12, s11
	s_ashr_i32 s11, s6, 3
	s_add_i32 s14, s10, s54
	s_mul_hi_i32 s13, s11, 0x6000
	s_mulk_i32 s11, 0x6000
	s_add_u32 s12, s34, s11
	v_or_b32_e32 v150, s14, v153
	s_addc_u32 s13, s35, s13
	v_ashrrev_i32_e32 v145, 31, v144
	v_ashrrev_i32_e32 v151, 31, v150
	v_lshl_add_u64 v[146:147], v[144:145], 2, s[12:13]
	s_movk_i32 s11, 0x2000
	v_lshlrev_b64 v[130:131], 10, v[150:151]
	v_add_co_u32_e32 v128, vcc, s11, v146
	v_lshl_add_u64 v[148:149], v[130:131], 0, v[144:145]
	s_nop 0
	v_addc_co_u32_e32 v129, vcc, 0, v147, vcc
	v_lshl_add_u64 v[158:159], v[148:149], 2, s[36:37]
	s_barrier
	global_load_dwordx4 v[140:143], v[128:129], off
	global_load_dwordx4 v[136:139], v[128:129], off offset:64
	global_load_dwordx4 v[132:135], v[128:129], off offset:512
	s_nop 0
	global_load_dwordx4 v[128:131], v[128:129], off offset:576
	s_mov_b64 s[98:99], 0x10000
	v_lshl_add_u64 v[178:179], v[158:159], 0, s[98:99]
	s_mov_b64 s[98:99], 0x20000
	v_lshl_add_u64 v[180:181], v[158:159], 0, s[98:99]
	s_mov_b64 s[98:99], 0x30000
	v_lshl_add_u64 v[182:183], v[158:159], 0, s[98:99]
	s_mov_b64 s[98:99], 0x80000
	v_lshl_add_u64 v[184:185], v[158:159], 0, s[98:99]
	s_mov_b64 s[98:99], 0x90000
	v_lshl_add_u64 v[186:187], v[158:159], 0, s[98:99]
	s_mov_b64 s[98:99], 0xa0000
	v_lshl_add_u64 v[188:189], v[158:159], 0, s[98:99]
	s_mov_b64 s[98:99], 0xb0000
	v_lshl_add_u64 v[190:191], v[158:159], 0, s[98:99]
	global_load_dwordx4 v[192:195], v[158:159], off nt
	global_load_dwordx4 v[196:199], v[158:159], off offset:64 nt
	global_load_dwordx4 v[200:203], v[158:159], off offset:512 nt
	global_load_dwordx4 v[204:207], v[158:159], off offset:576 nt
	global_load_dwordx4 v[208:211], v[178:179], off nt
	global_load_dwordx4 v[212:215], v[178:179], off offset:64 nt
	global_load_dwordx4 v[216:219], v[178:179], off offset:512 nt
	global_load_dwordx4 v[220:223], v[178:179], off offset:576 nt
	global_load_dwordx4 v[224:227], v[180:181], off nt
	global_load_dwordx4 v[228:231], v[180:181], off offset:64 nt
	global_load_dwordx4 v[232:235], v[180:181], off offset:512 nt
	global_load_dwordx4 v[236:239], v[180:181], off offset:576 nt
	v_lshl_add_u64 v[160:161], v[148:149], 1, s[0:1]
	s_mov_b64 s[12:13], 0x20000
	s_waitcnt vmcnt(11)
	v_pk_fma_f32 v[126:127], v[126:127], v[142:143], v[194:195]
	v_pk_fma_f32 v[124:125], v[124:125], v[140:141], v[192:193]
	s_nop 0
	v_cvt_pk_bf16_f32 v154, v124, v125
	v_cvt_pk_bf16_f32 v155, v126, v127
	global_store_dwordx2 v[160:161], v[154:155], off
	global_load_dwordx4 v[192:195], v[182:183], off nt
	s_waitcnt vmcnt(12)
	v_pk_fma_f32 v[122:123], v[122:123], v[138:139], v[198:199]
	v_pk_fma_f32 v[120:121], v[120:121], v[136:137], v[196:197]
	s_nop 0
	v_cvt_pk_bf16_f32 v154, v120, v121
	v_cvt_pk_bf16_f32 v155, v122, v123
	global_store_dwordx2 v[160:161], v[154:155], off offset:32
	global_load_dwordx4 v[196:199], v[182:183], off offset:64 nt
	s_waitcnt vmcnt(13)
	v_pk_fma_f32 v[118:119], v[118:119], v[134:135], v[202:203]
	v_pk_fma_f32 v[116:117], v[116:117], v[132:133], v[200:201]
	s_nop 0
	v_cvt_pk_bf16_f32 v154, v116, v117
	v_cvt_pk_bf16_f32 v155, v118, v119
	global_store_dwordx2 v[160:161], v[154:155], off offset:256
	global_load_dwordx4 v[200:203], v[182:183], off offset:512 nt
	v_or_b32_e32 v158, 16, v150
	v_ashrrev_i32_e32 v159, 31, v158
	v_lshlrev_b64 v[158:159], 10, v[158:159]
	v_lshl_add_u64 v[158:159], v[158:159], 0, v[144:145]
	v_lshl_add_u64 v[162:163], v[158:159], 2, s[36:37]
	v_lshl_add_u64 v[158:159], v[158:159], 1, s[0:1]
	s_waitcnt vmcnt(14)
	v_pk_fma_f32 v[110:111], v[110:111], v[130:131], v[206:207]
	v_pk_fma_f32 v[108:109], v[108:109], v[128:129], v[204:205]
	s_nop 0
	v_cvt_pk_bf16_f32 v154, v108, v109
	v_cvt_pk_bf16_f32 v155, v110, v111
	global_store_dwordx2 v[160:161], v[154:155], off offset:288
	global_load_dwordx4 v[204:207], v[182:183], off offset:576 nt
	v_or_b32_e32 v160, 32, v150
	v_ashrrev_i32_e32 v161, 31, v160
	v_lshlrev_b64 v[160:161], 10, v[160:161]
	v_lshl_add_u64 v[160:161], v[160:161], 0, v[144:145]
	v_or_b32_e32 v150, 48, v150
	v_ashrrev_i32_e32 v151, 31, v150
	v_lshlrev_b64 v[150:151], 10, v[150:151]
	v_lshl_add_u64 v[150:151], v[150:151], 0, v[144:145]
	s_waitcnt vmcnt(15)
	v_pk_fma_f32 v[114:115], v[114:115], v[142:143], v[210:211]
	v_pk_fma_f32 v[112:113], v[112:113], v[140:141], v[208:209]
	s_nop 0
	v_cvt_pk_bf16_f32 v154, v112, v113
	v_cvt_pk_bf16_f32 v155, v114, v115
	global_store_dwordx2 v[158:159], v[154:155], off
	global_load_dwordx4 v[208:211], v[184:185], off nt
	s_waitcnt vmcnt(16)
	v_pk_fma_f32 v[106:107], v[106:107], v[138:139], v[214:215]
	v_pk_fma_f32 v[104:105], v[104:105], v[136:137], v[212:213]
	s_nop 0
	v_cvt_pk_bf16_f32 v154, v104, v105
	v_cvt_pk_bf16_f32 v155, v106, v107
	global_store_dwordx2 v[158:159], v[154:155], off offset:32
	global_load_dwordx4 v[212:215], v[184:185], off offset:64 nt
	s_waitcnt vmcnt(17)
	v_pk_fma_f32 v[102:103], v[102:103], v[134:135], v[218:219]
	v_pk_fma_f32 v[100:101], v[100:101], v[132:133], v[216:217]
	s_nop 0
	v_cvt_pk_bf16_f32 v154, v100, v101
	v_cvt_pk_bf16_f32 v155, v102, v103
	global_store_dwordx2 v[158:159], v[154:155], off offset:256
	global_load_dwordx4 v[216:219], v[184:185], off offset:512 nt
	v_lshl_add_u64 v[162:163], v[160:161], 2, s[36:37]
	s_waitcnt vmcnt(18)
; __device__ __forceinline__ unsigned cvt_pk_bf16(float lo, float hi) { unsigned r; asm volatile("v_cvt_pk_bf16_f32 %0, %1, %2" : "=v"(r) : "v"(lo), "v"(hi)); return r; }
;     __device__ __forceinline__ void fused(f32x4 (&acc)[2][2][4][2], const Unit& u, int wr, int wc, int fr, int fq, LAS unsigned char* lds, int wid, int lane) const {
;     ...
;           for (int ai = 0; ai < 2; ++ai)
; #pragma unroll
;             for (int m = 0; m < 4; ++m) { const size_t off = (size_t)(row0 + ai * HALF + m * 16) * DM + col0;
; #pragma unroll
;                 for (int bj = 0; bj < 2; ++bj)
; #pragma unroll
;                     for (int n = 0; n < 2; ++n) { const f32x4 xv = *(const f32x4*)(base + off + bj * HALF + n * 16); const f32x4 o = xv + gv[bj][n] * acc[ai][bj][m][n];
;                         u32x2 w; w.x = cvt_pk_bf16(o[0], o[1]); w.y = cvt_pk_bf16(o[2], o[3]); *(u32x2*)(x1b + off + bj * HALF + n * 16) = w; acc[ai][bj][m][n] = o; }
;                 asm volatile("" ::: "memory"); } }
	v_pk_fma_f32 v[94:95], v[94:95], v[130:131], v[222:223]
	v_pk_fma_f32 v[92:93], v[92:93], v[128:129], v[220:221]
	s_nop 0
	v_cvt_pk_bf16_f32 v154, v92, v93
	v_cvt_pk_bf16_f32 v155, v94, v95
	global_store_dwordx2 v[158:159], v[154:155], off offset:288
	global_load_dwordx4 v[220:223], v[184:185], off offset:576 nt
	v_lshl_add_u64 v[158:159], v[160:161], 1, s[0:1]
	v_lshl_add_u64 v[160:161], v[150:151], 2, s[36:37]
	v_lshl_add_u64 v[150:151], v[150:151], 1, s[0:1]
	s_waitcnt vmcnt(19)
	v_pk_fma_f32 v[98:99], v[98:99], v[142:143], v[226:227]
	v_pk_fma_f32 v[96:97], v[96:97], v[140:141], v[224:225]
	s_nop 0
	v_cvt_pk_bf16_f32 v154, v96, v97
	v_cvt_pk_bf16_f32 v155, v98, v99
	global_store_dwordx2 v[158:159], v[154:155], off
	global_load_dwordx4 v[224:227], v[186:187], off nt
	s_waitcnt vmcnt(20)
	v_pk_fma_f32 v[90:91], v[90:91], v[138:139], v[230:231]
	v_pk_fma_f32 v[88:89], v[88:89], v[136:137], v[228:229]
	s_nop 0
	v_cvt_pk_bf16_f32 v154, v88, v89
	v_cvt_pk_bf16_f32 v155, v90, v91
	global_store_dwordx2 v[158:159], v[154:155], off offset:32
	global_load_dwordx4 v[228:231], v[186:187], off offset:64 nt
	s_waitcnt vmcnt(21)
	v_pk_fma_f32 v[86:87], v[86:87], v[134:135], v[234:235]
	v_pk_fma_f32 v[84:85], v[84:85], v[132:133], v[232:233]
	s_nop 0
	v_cvt_pk_bf16_f32 v154, v84, v85
	v_cvt_pk_bf16_f32 v155, v86, v87
	global_store_dwordx2 v[158:159], v[154:155], off offset:256
	global_load_dwordx4 v[232:235], v[186:187], off offset:512 nt
	s_waitcnt vmcnt(22)
	v_pk_fma_f32 v[78:79], v[78:79], v[130:131], v[238:239]
	v_pk_fma_f32 v[76:77], v[76:77], v[128:129], v[236:237]
	s_nop 0
	v_cvt_pk_bf16_f32 v154, v76, v77
	v_cvt_pk_bf16_f32 v155, v78, v79
	global_store_dwordx2 v[158:159], v[154:155], off offset:288
	global_load_dwordx4 v[236:239], v[186:187], off offset:576 nt
	v_lshl_add_u64 v[158:159], v[148:149], 0, s[12:13]
	s_mov_b64 s[12:13], 0x24000
	s_waitcnt vmcnt(22)
	v_pk_fma_f32 v[82:83], v[82:83], v[142:143], v[194:195]
	v_pk_fma_f32 v[80:81], v[80:81], v[140:141], v[192:193]
	s_nop 0
	v_cvt_pk_bf16_f32 v154, v80, v81
	v_cvt_pk_bf16_f32 v155, v82, v83
	global_store_dwordx2 v[150:151], v[154:155], off
	global_load_dwordx4 v[192:195], v[188:189], off nt
	s_waitcnt vmcnt(22)
	v_pk_fma_f32 v[74:75], v[74:75], v[138:139], v[198:199]
	v_pk_fma_f32 v[72:73], v[72:73], v[136:137], v[196:197]
	s_nop 0
	v_cvt_pk_bf16_f32 v154, v72, v73
	v_cvt_pk_bf16_f32 v155, v74, v75
	global_store_dwordx2 v[150:151], v[154:155], off offset:32
	global_load_dwordx4 v[196:199], v[188:189], off offset:64 nt
	s_waitcnt vmcnt(22)
	v_pk_fma_f32 v[70:71], v[70:71], v[134:135], v[202:203]
	v_pk_fma_f32 v[68:69], v[68:69], v[132:133], v[200:201]
	s_nop 0
	v_cvt_pk_bf16_f32 v154, v68, v69
	v_cvt_pk_bf16_f32 v155, v70, v71
	global_store_dwordx2 v[150:151], v[154:155], off offset:256
	global_load_dwordx4 v[200:203], v[188:189], off offset:512 nt
	v_lshl_add_u64 v[160:161], v[158:159], 2, s[36:37]
	s_waitcnt vmcnt(22)
	v_pk_fma_f32 v[66:67], v[66:67], v[130:131], v[206:207]
	v_pk_fma_f32 v[64:65], v[64:65], v[128:129], v[204:205]
	s_nop 0
	v_cvt_pk_bf16_f32 v154, v64, v65
	v_cvt_pk_bf16_f32 v155, v66, v67
	global_store_dwordx2 v[150:151], v[154:155], off offset:288
	global_load_dwordx4 v[204:207], v[188:189], off offset:576 nt
	v_lshl_add_u64 v[150:151], v[158:159], 1, s[0:1]
	v_lshl_add_u64 v[158:159], v[148:149], 0, s[12:13]
	s_mov_b64 s[12:13], 0x28000
	s_waitcnt vmcnt(22)
	v_pk_fma_f32 v[62:63], v[62:63], v[142:143], v[210:211]
	v_pk_fma_f32 v[60:61], v[60:61], v[140:141], v[208:209]
	s_nop 0
	v_cvt_pk_bf16_f32 v154, v60, v61
	v_cvt_pk_bf16_f32 v155, v62, v63
	global_store_dwordx2 v[150:151], v[154:155], off
	s_waitcnt vmcnt(21)
	v_pk_fma_f32 v[58:59], v[58:59], v[138:139], v[214:215]
	v_pk_fma_f32 v[56:57], v[56:57], v[136:137], v[212:213]
	s_nop 0
	v_cvt_pk_bf16_f32 v154, v56, v57
	v_cvt_pk_bf16_f32 v155, v58, v59
	global_store_dwordx2 v[150:151], v[154:155], off offset:32
	s_waitcnt vmcnt(20)
	v_pk_fma_f32 v[54:55], v[54:55], v[134:135], v[218:219]
	v_pk_fma_f32 v[52:53], v[52:53], v[132:133], v[216:217]
	s_nop 0
	v_cvt_pk_bf16_f32 v154, v52, v53
	v_cvt_pk_bf16_f32 v155, v54, v55
	global_store_dwordx2 v[150:151], v[154:155], off offset:256
	v_lshl_add_u64 v[160:161], v[158:159], 2, s[36:37]
	s_waitcnt vmcnt(19)
	v_pk_fma_f32 v[46:47], v[46:47], v[130:131], v[222:223]
	v_pk_fma_f32 v[44:45], v[44:45], v[128:129], v[220:221]
	s_nop 0
	v_cvt_pk_bf16_f32 v154, v44, v45
	v_cvt_pk_bf16_f32 v155, v46, v47
	global_store_dwordx2 v[150:151], v[154:155], off offset:288
	v_lshl_add_u64 v[150:151], v[158:159], 1, s[0:1]
	v_lshl_add_u64 v[158:159], v[148:149], 0, s[12:13]
	s_mov_b64 s[12:13], 0x2c000
	s_waitcnt vmcnt(18)
	v_pk_fma_f32 v[50:51], v[50:51], v[142:143], v[226:227]
	v_pk_fma_f32 v[48:49], v[48:49], v[140:141], v[224:225]
	s_nop 0
	v_cvt_pk_bf16_f32 v154, v48, v49
	v_cvt_pk_bf16_f32 v155, v50, v51
	global_store_dwordx2 v[150:151], v[154:155], off
	s_waitcnt vmcnt(17)
; #define LAS __attribute__((address_space(3)))
; __device__ __forceinline__ unsigned cvt_pk_bf16(float lo, float hi) { unsigned r; asm volatile("v_cvt_pk_bf16_f32 %0, %1, %2" : "=v"(r) : "v"(lo), "v"(hi)); return r; }
;     __device__ __forceinline__ void run(const f32x4 (&v)[2][2][4][2], const Unit& u, int wr, int wc, int fr, int fq, LAS unsigned char* lds, int wid, int lane) const {
;         LAS float* P = (LAS float*)lds; LAS float* S = (LAS float*)(lds + 4096);
; #pragma unroll
;         for (int ai = 0; ai < 2; ++ai)
; #pragma unroll
;             for (int m = 0; m < 4; ++m) { float s = 0.f;
; #pragma unroll
;                 for (int bj = 0; bj < 2; ++bj)
; #pragma unroll
;                     for (int n = 0; n < 2; ++n) { const f32x4 x = v[ai][bj][m][n]; s += (x[0] * x[0] + x[1] * x[1]) + (x[2] * x[2] + x[3] * x[3]); }
;                 s += __shfl_xor(s, 16); s += __shfl_xor(s, 32);
;                 if (fq == 0) P[(ai * HALF + wr * 64 + m * 16 + fr) * 4 + wc] = s; }
;     __device__ __forceinline__ void fused(f32x4 (&acc)[2][2][4][2], const Unit& u, int wr, int wc, int fr, int fq, LAS unsigned char* lds, int wid, int lane) const {
;     ...
;             for (int m = 0; m < 4; ++m) { const size_t off = (size_t)(row0 + ai * HALF + m * 16) * DM + col0;
; #pragma unroll
;                 for (int bj = 0; bj < 2; ++bj)
; #pragma unroll
;                     for (int n = 0; n < 2; ++n) { const f32x4 xv = *(const f32x4*)(base + off + bj * HALF + n * 16); const f32x4 o = xv + gv[bj][n] * acc[ai][bj][m][n];
;                         u32x2 w; w.x = cvt_pk_bf16(o[0], o[1]); w.y = cvt_pk_bf16(o[2], o[3]); *(u32x2*)(x1b + off + bj * HALF + n * 16) = w; acc[ai][bj][m][n] = o; }
;                 asm volatile("" ::: "memory"); } }
	v_pk_fma_f32 v[42:43], v[42:43], v[138:139], v[230:231]
	v_pk_fma_f32 v[40:41], v[40:41], v[136:137], v[228:229]
	s_nop 0
	v_cvt_pk_bf16_f32 v154, v40, v41
	v_cvt_pk_bf16_f32 v155, v42, v43
	global_store_dwordx2 v[150:151], v[154:155], off offset:32
	s_waitcnt vmcnt(16)
	v_pk_fma_f32 v[38:39], v[38:39], v[134:135], v[234:235]
	v_pk_fma_f32 v[36:37], v[36:37], v[132:133], v[232:233]
	s_nop 0
	v_cvt_pk_bf16_f32 v154, v36, v37
	v_cvt_pk_bf16_f32 v155, v38, v39
	global_store_dwordx2 v[150:151], v[154:155], off offset:256
	v_lshl_add_u64 v[160:161], v[158:159], 2, s[36:37]
	s_waitcnt vmcnt(15)
	v_pk_fma_f32 v[30:31], v[30:31], v[130:131], v[238:239]
	v_pk_fma_f32 v[28:29], v[28:29], v[128:129], v[236:237]
	s_nop 0
	v_cvt_pk_bf16_f32 v154, v28, v29
	v_cvt_pk_bf16_f32 v155, v30, v31
	global_store_dwordx2 v[150:151], v[154:155], off offset:288
	v_lshl_add_u64 v[150:151], v[158:159], 1, s[0:1]
	v_lshl_add_u64 v[158:159], v[148:149], 0, s[12:13]
	s_waitcnt vmcnt(14)
	v_pk_fma_f32 v[34:35], v[34:35], v[142:143], v[194:195]
	v_pk_fma_f32 v[32:33], v[32:33], v[140:141], v[192:193]
	s_nop 0
	v_cvt_pk_bf16_f32 v154, v32, v33
	v_cvt_pk_bf16_f32 v155, v34, v35
	global_store_dwordx2 v[150:151], v[154:155], off
	s_waitcnt vmcnt(13)
	v_pk_fma_f32 v[26:27], v[26:27], v[138:139], v[198:199]
	v_pk_fma_f32 v[24:25], v[24:25], v[136:137], v[196:197]
	s_nop 0
	v_cvt_pk_bf16_f32 v154, v24, v25
	v_cvt_pk_bf16_f32 v155, v26, v27
	global_store_dwordx2 v[150:151], v[154:155], off offset:32
	s_waitcnt vmcnt(12)
	v_pk_fma_f32 v[22:23], v[22:23], v[134:135], v[202:203]
	v_pk_fma_f32 v[20:21], v[20:21], v[132:133], v[200:201]
	s_nop 0
	v_cvt_pk_bf16_f32 v154, v20, v21
	v_cvt_pk_bf16_f32 v155, v22, v23
	global_store_dwordx2 v[150:151], v[154:155], off offset:256
	v_lshl_add_u64 v[160:161], v[158:159], 2, s[36:37]
	s_waitcnt vmcnt(11)
	v_pk_fma_f32 v[14:15], v[14:15], v[130:131], v[206:207]
	v_pk_fma_f32 v[12:13], v[12:13], v[128:129], v[204:205]
	v_lshl_add_u64 v[154:155], v[158:159], 1, s[0:1]
	v_cvt_pk_bf16_f32 v148, v12, v13
	v_cvt_pk_bf16_f32 v149, v14, v15
	global_store_dwordx2 v[150:151], v[148:149], off offset:288
	global_load_dwordx4 v[148:151], v[160:161], off nt
	s_lshl_b32 s0, s7, 2
	s_add_i32 s7, s0, 0
	s_waitcnt vmcnt(0)
	v_pk_fma_f32 v[142:143], v[18:19], v[142:143], v[150:151]
	v_pk_fma_f32 v[140:141], v[16:17], v[140:141], v[148:149]
	s_nop 0
	v_cvt_pk_bf16_f32 v16, v140, v141
	v_cvt_pk_bf16_f32 v17, v142, v143
	global_store_dwordx2 v[154:155], v[16:17], off
	global_load_dwordx4 v[148:151], v[160:161], off offset:64 nt
	s_waitcnt vmcnt(0)
	v_pk_fma_f32 v[16:17], v[10:11], v[138:139], v[150:151]
	v_pk_fma_f32 v[18:19], v[8:9], v[136:137], v[148:149]
	s_nop 0
	v_cvt_pk_bf16_f32 v8, v18, v19
	v_cvt_pk_bf16_f32 v9, v16, v17
	global_store_dwordx2 v[154:155], v[8:9], off offset:32
	global_load_dwordx4 v[136:139], v[160:161], off offset:512 nt
	s_waitcnt vmcnt(0)
	v_pk_fma_f32 v[8:9], v[6:7], v[134:135], v[138:139]
	v_pk_fma_f32 v[10:11], v[4:5], v[132:133], v[136:137]
	v_mul_f32_e32 v7, v127, v127
	v_cvt_pk_bf16_f32 v4, v10, v11
	v_cvt_pk_bf16_f32 v5, v8, v9
	global_store_dwordx2 v[154:155], v[4:5], off offset:256
	global_load_dwordx4 v[136:139], v[160:161], off offset:576 nt
	v_mbcnt_lo_u32_b32 v4, -1, 0
	v_mbcnt_hi_u32_b32 v4, -1, v4
	v_and_b32_e32 v6, 64, v4
	v_xor_b32_e32 v5, 16, v4
	v_add_u32_e32 v6, 64, v6
	v_cmp_lt_i32_e32 vcc, v5, v6
	v_fmac_f32_e32 v7, v126, v126
	v_mul_f32_e32 v134, v123, v123
	v_cndmask_b32_e32 v5, v4, v5, vcc
	v_lshlrev_b32_e32 v133, 2, v5
	v_mul_f32_e32 v5, v125, v125
	v_fmac_f32_e32 v5, v124, v124
	v_add_f32_e32 v5, v5, v7
	v_mul_f32_e32 v7, v121, v121
	v_fmac_f32_e32 v7, v120, v120
	v_fmac_f32_e32 v134, v122, v122
	v_add_f32_e32 v7, v7, v134
	v_add_f32_e32 v5, v5, v7
	v_mul_f32_e32 v7, v117, v117
	v_mul_f32_e32 v134, v119, v119
	v_fmac_f32_e32 v7, v116, v116
	v_fmac_f32_e32 v134, v118, v118
	v_add_f32_e32 v7, v7, v134
	v_add_f32_e32 v5, v5, v7
	v_mul_f32_e32 v7, v109, v109
	v_mul_f32_e32 v134, v111, v111
	v_fmac_f32_e32 v7, v108, v108
	v_fmac_f32_e32 v134, v110, v110
	v_add_f32_e32 v7, v7, v134
	v_add_f32_e32 v5, v5, v7
	ds_bpermute_b32 v7, v133, v5
	v_xor_b32_e32 v134, 32, v4
	v_cmp_lt_i32_e32 vcc, v134, v6
	v_and_b32_e32 v132, 63, v170
	s_waitcnt lgkmcnt(0)
	v_add_f32_e32 v135, v5, v7
	v_cndmask_b32_e32 v4, v4, v134, vcc
	v_lshlrev_b32_e32 v134, 2, v4
	v_cmp_gt_u32_e32 vcc, 16, v132
	s_waitcnt vmcnt(0)
	v_pk_fma_f32 v[6:7], v[0:1], v[128:129], v[136:137]
	s_nop 0
	v_cvt_pk_bf16_f32 v0, v6, v7
	v_pk_fma_f32 v[4:5], v[2:3], v[130:131], v[138:139]
	s_nop 0
	v_cvt_pk_bf16_f32 v1, v4, v5
	global_store_dwordx2 v[154:155], v[0:1], off offset:288
	ds_bpermute_b32 v0, v134, v135
	s_and_saveexec_b64 s[0:1], vcc
	v_readlane_b32 s56, v240, 6
	v_readlane_b32 s58, v240, 8
	v_readlane_b32 s57, v240, 7
	v_readlane_b32 s59, v240, 9
	s_cbranch_execz .LBB0_584
	s_lshl_b32 s11, s51, 10
	s_add_i32 s11, s7, s11
	v_lshl_add_u32 v1, v153, 4, s11
	s_waitcnt lgkmcnt(0)
	v_add_f32_e32 v0, v135, v0
	ds_write_b32 v1, v0
